# XCD barrier: the CU L1 invalidate is issued while the workgroup waits (after its arrival atomic / with the release write-back) instead of after the release
# speedup vs baseline: 1.0028x; 1.0028x over previous
.LBB0_96:
	s_or_b64 exec, exec, s[8:9]
	v_cvt_f32_u32_e32 v4, v2
	s_waitcnt vmcnt(0)
	v_readfirstlane_b32 s1, v3
	v_sub_u32_e32 v3, 0, v2
	v_rcp_iflag_f32_e32 v4, v4
	v_add_u32_e32 v5, s1, v1
	v_mul_f32_e32 v4, 0x4f7ffffe, v4
	v_cvt_u32_f32_e32 v4, v4
	v_mul_lo_u32 v1, v3, v4
	v_mul_hi_u32 v1, v4, v1
	v_add_u32_e32 v1, v4, v1
	v_mul_hi_u32 v1, v5, v1
	v_mul_lo_u32 v3, v1, v2
	v_sub_u32_e32 v3, v5, v3
	v_add_u32_e32 v4, 1, v1
	v_cmp_ge_u32_e32 vcc, v3, v2
	s_nop 1
	v_cndmask_b32_e32 v1, v1, v4, vcc
	v_sub_u32_e32 v4, v3, v2
	v_cndmask_b32_e32 v3, v3, v4, vcc
	v_add_u32_e32 v4, 1, v1
	v_cmp_ge_u32_e32 vcc, v3, v2
	v_add_u32_e32 v3, 1, v5
	s_nop 0
	v_cndmask_b32_e32 v1, v1, v4, vcc
	v_mul_lo_u32 v4, v2, v1
	v_add_u32_e32 v2, v4, v2
	v_cmp_ne_u32_e32 vcc, v3, v2
	s_and_saveexec_b64 s[6:7], vcc
	s_xor_b64 s[6:7], exec, s[6:7]
	s_cbranch_execz .LBB0_110
	s_waitcnt lgkmcnt(0)
	buffer_inv sc1
	v_readlane_b32 s98, v254, 38
	s_nop 3
	s_lshl_b32 s98, s98, 8
	s_sub_u32 s98, s4, s98
	s_subb_u32 s99, s5, 0
	s_add_u32 s14, s98, 0x3400
	s_addc_u32 s15, s99, 0
	v_mad_u32_u24 v1, v1, v0, v0
	v_mov_b32_e32 v0, 0
	global_load_dword v0, v0, s[14:15] sc1
	s_waitcnt vmcnt(0)
	v_cmp_lt_u32_e32 vcc, v0, v1
	s_and_saveexec_b64 s[8:9], vcc
	s_cbranch_execz .LBB0_109
	s_add_u32 s10, s78, 0x80200
	s_addc_u32 s11, s79, 0
	s_mov_b32 s1, 1
	s_mov_b64 s[16:17], 0
	v_mov_b32_e32 v0, 0
	s_branch .LBB0_100

.LBB0_109:
	s_or_b64 exec, exec, s[8:9]
	s_waitcnt vmcnt(0)
	s_waitcnt vmcnt(0)
.LBB0_110:
	s_andn2_saveexec_b64 s[6:7], s[6:7]
	s_cbranch_execz .LBB0_130
	s_mov_b64 s[6:7], exec
	buffer_wbl2 sc1
	buffer_inv sc1
	s_waitcnt lgkmcnt(0)
	s_waitcnt vmcnt(0)
	v_mbcnt_lo_u32_b32 v1, s6, 0
	v_mbcnt_hi_u32_b32 v1, s7, v1
	v_cmp_eq_u32_e32 vcc, 0, v1
	s_and_saveexec_b64 s[8:9], vcc
	s_cbranch_execz .LBB0_113
	s_bcnt1_i32_b64 s1, s[6:7]
	v_mov_b32_e32 v2, 0x83000
	v_mov_b32_e32 v3, s1
	global_atomic_add v2, v2, v3, s[78:79] offset:1024 sc0

.LBB0_127:
	s_or_b64 exec, exec, s[6:7]
	s_mov_b64 s[6:7], exec
	v_mbcnt_lo_u32_b32 v0, s6, 0
	v_mbcnt_hi_u32_b32 v0, s7, v0
	v_cmp_eq_u32_e32 vcc, 0, v0
	s_waitcnt vmcnt(0)
	s_and_saveexec_b64 s[8:9], vcc
	s_cbranch_execz .LBB0_129
	s_bcnt1_i32_b64 s1, s[6:7]
	v_mov_b32_e32 v0, 0x2000
	v_mov_b32_e32 v1, s1

.LBB0_217:
	s_or_b64 exec, exec, s[8:9]
	v_cvt_f32_u32_e32 v4, v2
	s_waitcnt vmcnt(0)
	v_readfirstlane_b32 s1, v3
	v_sub_u32_e32 v3, 0, v2
	v_rcp_iflag_f32_e32 v4, v4
	v_add_u32_e32 v5, s1, v1
	v_mul_f32_e32 v4, 0x4f7ffffe, v4
	v_cvt_u32_f32_e32 v4, v4
	v_mul_lo_u32 v1, v3, v4
	v_mul_hi_u32 v1, v4, v1
	v_add_u32_e32 v1, v4, v1
	v_mul_hi_u32 v1, v5, v1
	v_mul_lo_u32 v3, v1, v2
	v_sub_u32_e32 v3, v5, v3
	v_add_u32_e32 v4, 1, v1
	v_cmp_ge_u32_e32 vcc, v3, v2
	s_nop 1
	v_cndmask_b32_e32 v1, v1, v4, vcc
	v_sub_u32_e32 v4, v3, v2
	v_cndmask_b32_e32 v3, v3, v4, vcc
	v_add_u32_e32 v4, 1, v1
	v_cmp_ge_u32_e32 vcc, v3, v2
	v_add_u32_e32 v3, 1, v5
	s_nop 0
	v_cndmask_b32_e32 v1, v1, v4, vcc
	v_mul_lo_u32 v4, v2, v1
	v_add_u32_e32 v2, v4, v2
	v_cmp_ne_u32_e32 vcc, v3, v2
	s_and_saveexec_b64 s[6:7], vcc
	s_xor_b64 s[6:7], exec, s[6:7]
	s_cbranch_execz .LBB0_231
	s_waitcnt lgkmcnt(0)
	buffer_inv sc1
	v_readlane_b32 s98, v254, 38
	s_nop 3
	s_lshl_b32 s98, s98, 8
	s_sub_u32 s98, s4, s98
	s_subb_u32 s99, s5, 0
	s_add_u32 s16, s98, 0x3400
	s_addc_u32 s17, s99, 0
	v_mad_u32_u24 v1, v1, v0, v0
	v_mov_b32_e32 v0, 0
	global_load_dword v0, v0, s[16:17] sc1
	s_waitcnt vmcnt(0)
	v_cmp_lt_u32_e32 vcc, v0, v1
	s_and_saveexec_b64 s[8:9], vcc
	s_cbranch_execz .LBB0_230
	s_add_u32 s10, s78, 0x80200
	s_addc_u32 s11, s79, 0
	s_mov_b32 s1, 1
	s_mov_b64 s[18:19], 0
	v_mov_b32_e32 v0, 0
	s_branch .LBB0_221

.LBB0_759:
	s_or_b64 exec, exec, s[6:7]
	v_cvt_f32_u32_e32 v4, v2
	s_waitcnt vmcnt(0)
	v_readfirstlane_b32 s4, v3
	v_sub_u32_e32 v3, 0, v2
	v_rcp_iflag_f32_e32 v4, v4
	v_add_u32_e32 v5, s4, v1
	v_mul_f32_e32 v4, 0x4f7ffffe, v4
	v_cvt_u32_f32_e32 v4, v4
	v_mul_lo_u32 v1, v3, v4
	v_mul_hi_u32 v1, v4, v1
	v_add_u32_e32 v1, v4, v1
	v_mul_hi_u32 v1, v5, v1
	v_mul_lo_u32 v3, v1, v2
	v_sub_u32_e32 v3, v5, v3
	v_add_u32_e32 v4, 1, v1
	v_cmp_ge_u32_e32 vcc, v3, v2
	s_nop 1
	v_cndmask_b32_e32 v1, v1, v4, vcc
	v_sub_u32_e32 v4, v3, v2
	v_cndmask_b32_e32 v3, v3, v4, vcc
	v_add_u32_e32 v4, 1, v1
	v_cmp_ge_u32_e32 vcc, v3, v2
	v_add_u32_e32 v3, 1, v5
	s_nop 0
	v_cndmask_b32_e32 v1, v1, v4, vcc
	v_mul_lo_u32 v4, v2, v1
	v_add_u32_e32 v2, v4, v2
	v_cmp_ne_u32_e32 vcc, v3, v2
	s_and_saveexec_b64 s[4:5], vcc
	s_xor_b64 s[4:5], exec, s[4:5]
	s_cbranch_execz .LBB0_773
	s_waitcnt lgkmcnt(0)
	buffer_inv sc1
	v_readlane_b32 s98, v254, 38
	s_nop 3
	s_lshl_b32 s98, s98, 8
	s_sub_u32 s98, s2, s98
	s_subb_u32 s99, s3, 0
	s_add_u32 s10, s98, 0x3400
	s_addc_u32 s11, s99, 0
	v_mad_u32_u24 v1, v1, v0, v0
	v_mov_b32_e32 v0, 0
	global_load_dword v0, v0, s[10:11] sc1
	s_waitcnt vmcnt(0)
	v_cmp_lt_u32_e32 vcc, v0, v1
	s_and_saveexec_b64 s[6:7], vcc
	s_cbranch_execz .LBB0_772
	s_add_u32 s8, s78, 0x80200
	s_addc_u32 s9, s79, 0
	s_mov_b32 s22, 1
	s_mov_b64 s[12:13], 0
	v_mov_b32_e32 v0, 0
	s_branch .LBB0_763

.LBB0_772:
	s_or_b64 exec, exec, s[6:7]
	s_waitcnt vmcnt(0)
	s_waitcnt vmcnt(0)
.LBB0_773:
	s_andn2_saveexec_b64 s[4:5], s[4:5]
	s_cbranch_execz .LBB0_793
	s_mov_b64 s[4:5], exec
	buffer_wbl2 sc1
	buffer_inv sc1
	s_waitcnt lgkmcnt(0)
	s_waitcnt vmcnt(0)
	v_mbcnt_lo_u32_b32 v1, s4, 0
	v_mbcnt_hi_u32_b32 v1, s5, v1
	v_cmp_eq_u32_e32 vcc, 0, v1
	s_and_saveexec_b64 s[6:7], vcc
	s_cbranch_execz .LBB0_776
	s_bcnt1_i32_b64 s4, s[4:5]
	v_mov_b32_e32 v2, 0x83000
	v_mov_b32_e32 v3, s4
	global_atomic_add v2, v2, v3, s[78:79] offset:1024 sc0

.LBB0_790:
	s_or_b64 exec, exec, s[4:5]
	s_mov_b64 s[4:5], exec
	v_mbcnt_lo_u32_b32 v0, s4, 0
	v_mbcnt_hi_u32_b32 v0, s5, v0
	v_cmp_eq_u32_e32 vcc, 0, v0
	s_waitcnt vmcnt(0)
	s_and_saveexec_b64 s[6:7], vcc
	s_cbranch_execz .LBB0_792
	s_bcnt1_i32_b64 s4, s[4:5]
	v_mov_b32_e32 v0, 0x2000
	v_mov_b32_e32 v1, s4

.LBB0_1020:
	s_or_b64 exec, exec, s[8:9]
	v_cvt_f32_u32_e32 v4, v2
	s_waitcnt vmcnt(0)
	v_readfirstlane_b32 s6, v3
	v_sub_u32_e32 v3, 0, v2
	v_rcp_iflag_f32_e32 v4, v4
	v_add_u32_e32 v5, s6, v1
	v_mul_f32_e32 v4, 0x4f7ffffe, v4
	v_cvt_u32_f32_e32 v4, v4
	v_mul_lo_u32 v1, v3, v4
	v_mul_hi_u32 v1, v4, v1
	v_add_u32_e32 v1, v4, v1
	v_mul_hi_u32 v1, v5, v1
	v_mul_lo_u32 v3, v1, v2
	v_sub_u32_e32 v3, v5, v3
	v_add_u32_e32 v4, 1, v1
	v_cmp_ge_u32_e32 vcc, v3, v2
	s_nop 1
	v_cndmask_b32_e32 v1, v1, v4, vcc
	v_sub_u32_e32 v4, v3, v2
	v_cndmask_b32_e32 v3, v3, v4, vcc
	v_add_u32_e32 v4, 1, v1
	v_cmp_ge_u32_e32 vcc, v3, v2
	v_add_u32_e32 v3, 1, v5
	s_nop 0
	v_cndmask_b32_e32 v1, v1, v4, vcc
	v_mul_lo_u32 v4, v2, v1
	v_add_u32_e32 v2, v4, v2
	v_cmp_ne_u32_e32 vcc, v3, v2
	s_and_saveexec_b64 s[6:7], vcc
	s_xor_b64 s[6:7], exec, s[6:7]
	s_cbranch_execz .LBB0_1034
	s_waitcnt lgkmcnt(0)
	buffer_inv sc1
	v_readlane_b32 s98, v254, 38
	s_nop 3
	s_lshl_b32 s98, s98, 8
	s_sub_u32 s98, s4, s98
	s_subb_u32 s99, s5, 0
	s_add_u32 s12, s98, 0x3400
	s_addc_u32 s13, s99, 0
	v_mad_u32_u24 v1, v1, v0, v0
	v_mov_b32_e32 v0, 0
	global_load_dword v0, v0, s[12:13] sc1
	s_waitcnt vmcnt(0)
	v_cmp_lt_u32_e32 vcc, v0, v1
	s_and_saveexec_b64 s[8:9], vcc
	s_cbranch_execz .LBB0_1033
	s_add_u32 s10, s78, 0x80200
	s_addc_u32 s11, s79, 0
	s_mov_b32 s24, 1
	s_mov_b64 s[14:15], 0
	v_mov_b32_e32 v0, 0
	s_branch .LBB0_1024

.LBB0_1034:
	s_andn2_saveexec_b64 s[6:7], s[6:7]
	s_cbranch_execz .LBB0_1054
	s_mov_b64 s[6:7], exec
	buffer_wbl2 sc1
	buffer_inv sc1
	s_waitcnt lgkmcnt(0)
	s_waitcnt vmcnt(0)
	v_mbcnt_lo_u32_b32 v1, s6, 0
	v_mbcnt_hi_u32_b32 v1, s7, v1
	v_cmp_eq_u32_e32 vcc, 0, v1
	s_and_saveexec_b64 s[8:9], vcc
	s_cbranch_execz .LBB0_1037
	s_bcnt1_i32_b64 s6, s[6:7]
	v_mov_b32_e32 v2, 0x83000
	v_mov_b32_e32 v3, s6
	global_atomic_add v2, v2, v3, s[78:79] offset:1024 sc0

.LBB0_1051:
	s_or_b64 exec, exec, s[6:7]
	s_mov_b64 s[6:7], exec
	v_mbcnt_lo_u32_b32 v0, s6, 0
	v_mbcnt_hi_u32_b32 v0, s7, v0
	v_cmp_eq_u32_e32 vcc, 0, v0
	s_waitcnt vmcnt(0)
	s_and_saveexec_b64 s[8:9], vcc
	s_cbranch_execz .LBB0_1053
	s_bcnt1_i32_b64 s6, s[6:7]
	v_mov_b32_e32 v0, 0x2000
	v_mov_b32_e32 v1, s6

.LBB0_1114:
	s_or_b64 exec, exec, s[6:7]
	v_cvt_f32_u32_e32 v4, v2
	s_waitcnt vmcnt(0)
	v_readfirstlane_b32 s4, v3
	v_sub_u32_e32 v3, 0, v2
	v_rcp_iflag_f32_e32 v4, v4
	v_add_u32_e32 v5, s4, v1
	v_mul_f32_e32 v4, 0x4f7ffffe, v4
	v_cvt_u32_f32_e32 v4, v4
	v_mul_lo_u32 v1, v3, v4
	v_mul_hi_u32 v1, v4, v1
	v_add_u32_e32 v1, v4, v1
	v_mul_hi_u32 v1, v5, v1
	v_mul_lo_u32 v3, v1, v2
	v_sub_u32_e32 v3, v5, v3
	v_add_u32_e32 v4, 1, v1
	v_cmp_ge_u32_e32 vcc, v3, v2
	s_nop 1
	v_cndmask_b32_e32 v1, v1, v4, vcc
	v_sub_u32_e32 v4, v3, v2
	v_cndmask_b32_e32 v3, v3, v4, vcc
	v_add_u32_e32 v4, 1, v1
	v_cmp_ge_u32_e32 vcc, v3, v2
	v_add_u32_e32 v3, 1, v5
	s_nop 0
	v_cndmask_b32_e32 v1, v1, v4, vcc
	v_mul_lo_u32 v4, v2, v1
	v_add_u32_e32 v2, v4, v2
	v_cmp_ne_u32_e32 vcc, v3, v2
	s_and_saveexec_b64 s[4:5], vcc
	s_xor_b64 s[4:5], exec, s[4:5]
	s_cbranch_execz .LBB0_1128
	s_waitcnt lgkmcnt(0)
	buffer_inv sc1
	v_readlane_b32 s98, v254, 38
	s_nop 3
	s_lshl_b32 s98, s98, 8
	s_sub_u32 s98, s2, s98
	s_subb_u32 s99, s3, 0
	s_add_u32 s10, s98, 0x3400
	s_addc_u32 s11, s99, 0
	v_mad_u32_u24 v1, v1, v0, v0
	v_mov_b32_e32 v0, 0
	global_load_dword v0, v0, s[10:11] sc1
	s_waitcnt vmcnt(0)
	v_cmp_lt_u32_e32 vcc, v0, v1
	s_and_saveexec_b64 s[6:7], vcc
	s_cbranch_execz .LBB0_1127
	s_add_u32 s8, s78, 0x80200
	s_addc_u32 s9, s79, 0
	s_mov_b32 s24, 1
	s_mov_b64 s[14:15], 0
	v_mov_b32_e32 v0, 0
	s_branch .LBB0_1118

.LBB0_1244:
	s_or_b64 exec, exec, s[6:7]
	v_cvt_f32_u32_e32 v4, v2
	s_waitcnt vmcnt(0)
	v_readfirstlane_b32 s4, v3
	v_sub_u32_e32 v3, 0, v2
	v_rcp_iflag_f32_e32 v4, v4
	v_add_u32_e32 v5, s4, v1
	v_mul_f32_e32 v4, 0x4f7ffffe, v4
	v_cvt_u32_f32_e32 v4, v4
	v_mul_lo_u32 v1, v3, v4
	v_mul_hi_u32 v1, v4, v1
	v_add_u32_e32 v1, v4, v1
	v_mul_hi_u32 v1, v5, v1
	v_mul_lo_u32 v3, v1, v2
	v_sub_u32_e32 v3, v5, v3
	v_add_u32_e32 v4, 1, v1
	v_cmp_ge_u32_e32 vcc, v3, v2
	s_nop 1
	v_cndmask_b32_e32 v1, v1, v4, vcc
	v_sub_u32_e32 v4, v3, v2
	v_cndmask_b32_e32 v3, v3, v4, vcc
	v_add_u32_e32 v4, 1, v1
	v_cmp_ge_u32_e32 vcc, v3, v2
	v_add_u32_e32 v3, 1, v5
	s_nop 0
	v_cndmask_b32_e32 v1, v1, v4, vcc
	v_mul_lo_u32 v4, v2, v1
	v_add_u32_e32 v2, v4, v2
	v_cmp_ne_u32_e32 vcc, v3, v2
	s_and_saveexec_b64 s[4:5], vcc
	s_xor_b64 s[4:5], exec, s[4:5]
	s_cbranch_execz .LBB0_1258
	s_waitcnt lgkmcnt(0)
	buffer_inv sc1
	v_readlane_b32 s98, v254, 38
	s_nop 3
	s_lshl_b32 s98, s98, 8
	s_sub_u32 s98, s2, s98
	s_subb_u32 s99, s3, 0
	s_add_u32 s10, s98, 0x3400
	s_addc_u32 s11, s99, 0
	v_mad_u32_u24 v1, v1, v0, v0
	v_mov_b32_e32 v0, 0
	global_load_dword v0, v0, s[10:11] sc1
	s_waitcnt vmcnt(0)
	v_cmp_lt_u32_e32 vcc, v0, v1
	s_and_saveexec_b64 s[6:7], vcc
	s_cbranch_execz .LBB0_1257
	s_add_u32 s8, s78, 0x80200
	s_addc_u32 s9, s79, 0
	s_mov_b32 s26, 1
	s_mov_b64 s[16:17], 0
	v_mov_b32_e32 v0, 0
	s_branch .LBB0_1248
